# v19 + hgrn_m1 / hgrn_m3 chunk loops: the barrier at the end of a chunk removed (only the Tl write separates it from the next chunk's first barrier)
# speedup vs baseline: 1.0101x; 1.0100x over previous
; #define LAS __attribute__((address_space(3)))
; __device__ __forceinline__ void hgrn_m1(Frame& F) {
;     ...
;             __syncthreads();
; #pragma unroll
;             for (int g4 = 0; g4 < 4; ++g4) { const f32x4 d4 = *(const LAS f32x4*)(Dl + 32 * kt + 8 * g4 + 4 * hi);
; #pragma unroll
;                 for (int x = 0; x < 2; ++x)
; #pragma unroll
;                     for (int j = 0; j < 4; ++j) st[x][4 * g4 + j] *= d4[j]; }
; #pragma unroll
;             for (int s2 = 0; s2 < 4; ++s2) {
;                 const bf16x8 a = *(const LAS bf16x8*)(KT + (32 * kt + r32) * P64 + (8 * hi + 16 * s2) * 2);
; #pragma unroll
;                 for (int x = 0; x < 2; ++x) { const bf16x8 bb = *(const LAS bf16x8*)(VT + (32 * (vt0 + x) + r32) * P64 + (8 * hi + 16 * s2) * 2);
;                     st[x] = __builtin_amdgcn_mfma_f32_32x32x16_bf16(a, bb, st[x], 0, 0, 0); }
;             }
;             __syncthreads();
.LBB0_287:
	v_add_u32_e32 v41, s2, v64
	s_waitcnt lgkmcnt(0)
	s_barrier
	ds_read_b128 v[44:47], v41 offset:38912
	ds_read_b128 v[92:95], v41 offset:38944
	s_add_i32 s26, s26, 1
	s_cmp_eq_u32 s26, 16
	s_waitcnt lgkmcnt(1)
	v_pk_mul_f32 v[2:3], v[2:3], v[44:45]
	v_pk_mul_f32 v[4:5], v[4:5], v[46:47]
	v_pk_mul_f32 v[18:19], v[18:19], v[44:45]
	v_pk_mul_f32 v[20:21], v[20:21], v[46:47]
	ds_read_b128 v[44:47], v41 offset:38976
	s_waitcnt lgkmcnt(1)
	v_pk_mul_f32 v[6:7], v[6:7], v[92:93]
	v_pk_mul_f32 v[8:9], v[8:9], v[94:95]
	v_pk_mul_f32 v[22:23], v[22:23], v[92:93]
	v_pk_mul_f32 v[24:25], v[24:25], v[94:95]
	s_waitcnt lgkmcnt(0)
	v_pk_mul_f32 v[10:11], v[10:11], v[44:45]
	v_pk_mul_f32 v[12:13], v[12:13], v[46:47]
	v_pk_mul_f32 v[26:27], v[26:27], v[44:45]
	v_pk_mul_f32 v[28:29], v[28:29], v[46:47]
	ds_read_b128 v[44:47], v41 offset:39008
	s_waitcnt lgkmcnt(0)
	v_pk_mul_f32 v[14:15], v[14:15], v[44:45]
	v_pk_mul_f32 v[16:17], v[16:17], v[46:47]
	v_pk_mul_f32 v[30:31], v[30:31], v[44:45]
	v_pk_mul_f32 v[32:33], v[32:33], v[46:47]
	ds_read_b128 v[44:47], v75
	ds_read_b128 v[92:95], v75 offset:32
	ds_read_b128 v[96:99], v76 offset:18432
	ds_read_b128 v[100:103], v76 offset:18464
	s_waitcnt lgkmcnt(1)
	v_mfma_f32_32x32x16_bf16 v[2:17], v[44:47], v[96:99], v[2:17]
	ds_read_b128 v[96:99], v77 offset:18432
	ds_read_b128 v[104:107], v77 offset:18464
	s_waitcnt lgkmcnt(1)
	v_mfma_f32_32x32x16_bf16 v[18:33], v[44:47], v[96:99], v[18:33]
	v_mfma_f32_32x32x16_bf16 v[2:17], v[92:95], v[100:103], v[2:17]
	s_waitcnt lgkmcnt(0)
	v_mfma_f32_32x32x16_bf16 v[18:33], v[92:95], v[104:107], v[18:33]
	ds_read_b128 v[44:47], v75 offset:64
	ds_read_b128 v[92:95], v76 offset:18496
	s_waitcnt lgkmcnt(0)
	v_mfma_f32_32x32x16_bf16 v[2:17], v[44:47], v[92:95], v[2:17]
	ds_read_b128 v[92:95], v77 offset:18496
	s_waitcnt lgkmcnt(0)
	v_mfma_f32_32x32x16_bf16 v[18:33], v[44:47], v[92:95], v[18:33]
	ds_read_b128 v[44:47], v75 offset:96
	ds_read_b128 v[92:95], v76 offset:18528
	s_waitcnt lgkmcnt(0)
	v_mfma_f32_32x32x16_bf16 v[2:17], v[44:47], v[92:95], v[2:17]
	ds_read_b128 v[92:95], v77 offset:18528
	s_waitcnt lgkmcnt(0)
	v_mfma_f32_32x32x16_bf16 v[18:33], v[44:47], v[92:95], v[18:33]
	s_cbranch_scc1 .LBB0_300

; __device__ __forceinline__ unsigned f2bf(float f) { return cvt_pk_bf16(f, 0.f) & 0xffffu; }
; __device__ __forceinline__ void hgrn_m3(Frame& F) {
;     ...
;         __syncthreads();
; #pragma unroll
;         for (int r = 0; r < 4; ++r) {
;             const int t = 16 * wi + 4 * g + r;
;             const float tot = SS[t] + SS[64 + t];
;             const float rstd = 1.0f / sqrtf(tot * (1.0f / 128.0f) + RMS_EPS);
; #pragma unroll
;             for (int vt = 0; vt < 4; ++vt) HB[(t0 + t) * D + 128 * h + 64 * vh + 16 * vt + c16] = (unsigned short)f2bf(o[vt][r] * rstd * bf2f(gv[vt][r]));
.LBB0_444:
	s_or_b64 exec, exec, s[24:25]
	s_waitcnt lgkmcnt(0)
	s_barrier
	ds_read_b128 v[50:53], v151
	ds_read_b128 v[54:57], v151 offset:256
	s_add_i32 s77, s77, 1
	s_add_i32 s86, s86, 64
	s_cmp_eq_u32 s77, 16
	s_waitcnt lgkmcnt(0)
	v_add_f32_e32 v50, v50, v54
	v_fmamk_f32 v50, v50, 0x3c000000, v252
	v_mul_f32_e32 v54, 0x4f800000, v50
	v_cmp_gt_f32_e32 vcc, s85, v50
	s_nop 1
	v_cndmask_b32_e32 v50, v50, v54, vcc
	v_sqrt_f32_e32 v54, v50
	s_nop 0
	v_add_u32_e32 v58, -1, v54
	v_fma_f32 v60, -v58, v54, v50
	v_add_u32_e32 v59, 1, v54
	v_cmp_ge_f32_e64 s[62:63], 0, v60
	s_nop 1
	v_cndmask_b32_e64 v58, v54, v58, s[62:63]
	v_fma_f32 v54, -v59, v54, v50
	v_cmp_lt_f32_e64 s[62:63], 0, v54
	s_nop 1
	v_cndmask_b32_e64 v54, v58, v59, s[62:63]
	v_mul_f32_e32 v58, 0x37800000, v54
	v_cndmask_b32_e32 v54, v54, v58, vcc
	v_cmp_class_f32_e32 vcc, v50, v220
	s_nop 1
	v_cndmask_b32_e32 v50, v54, v50, vcc
	v_div_scale_f32 v54, s[24:25], v50, v50, 1.0
	v_rcp_f32_e32 v58, v54
	s_nop 0
	v_fma_f32 v59, -v54, v58, 1.0
	v_fmac_f32_e32 v58, v59, v58
	v_div_scale_f32 v59, vcc, 1.0, v50, 1.0
	v_mul_f32_e32 v60, v59, v58
	v_fma_f32 v61, -v54, v60, v59
	v_fmac_f32_e32 v60, v61, v58
	v_fma_f32 v54, -v54, v60, v59
	v_div_fmas_f32 v54, v54, v58, v60
	v_div_fixup_f32 v50, v54, v50, 1.0
	v_mul_f32_e32 v34, v34, v50
	s_waitcnt vmcnt(15)
	v_lshlrev_b32_e32 v54, 16, v187
	v_lshlrev_b64 v[58:59], 11, v[98:99]
	v_mul_f32_e32 v34, v34, v54
	v_lshl_add_u64 v[58:59], v[96:97], 0, v[58:59]
	v_cvt_pk_bf16_f32 v34, v34, s0
	global_store_short v[58:59], v34, off
	v_mul_f32_e32 v34, v38, v50
	s_waitcnt vmcnt(14)
	v_lshlrev_b32_e32 v38, 16, v186
	v_mul_f32_e32 v34, v34, v38
	v_cvt_pk_bf16_f32 v34, v34, s0
	global_store_short v[58:59], v34, off offset:32
	v_mul_f32_e32 v34, v42, v50
	s_waitcnt vmcnt(13)
	v_lshlrev_b32_e32 v38, 16, v185
	v_mul_f32_e32 v34, v34, v38
	v_add_f32_e32 v38, v51, v55
	v_fmamk_f32 v38, v38, 0x3c000000, v252
	v_mul_f32_e32 v42, 0x4f800000, v38
	v_cmp_gt_f32_e32 vcc, s85, v38
	v_cvt_pk_bf16_f32 v34, v34, s0
	global_store_short v[58:59], v34, off offset:64
	v_cndmask_b32_e32 v38, v38, v42, vcc
	v_sqrt_f32_e32 v42, v38
	v_mul_f32_e32 v34, v46, v50
	s_waitcnt vmcnt(11)
	v_lshlrev_b32_e32 v46, 16, v184
	v_mul_f32_e32 v34, v34, v46
	v_add_u32_e32 v50, -1, v42
	v_fma_f32 v51, -v50, v42, v38
	v_cmp_ge_f32_e64 s[62:63], 0, v51
	v_add_u32_e32 v51, 1, v42
	v_cvt_pk_bf16_f32 v34, v34, s0
	v_cndmask_b32_e64 v50, v42, v50, s[62:63]
	v_fma_f32 v42, -v51, v42, v38
	v_cmp_lt_f32_e64 s[62:63], 0, v42
	global_store_short v[58:59], v34, off offset:96
	s_nop 0
	v_cndmask_b32_e64 v42, v50, v51, s[62:63]
	v_mul_f32_e32 v50, 0x37800000, v42
	v_cndmask_b32_e32 v42, v42, v50, vcc
	v_cmp_class_f32_e32 vcc, v38, v220
	s_nop 1
	v_cndmask_b32_e32 v38, v42, v38, vcc
	v_div_scale_f32 v42, s[24:25], v38, v38, 1.0
	v_rcp_f32_e32 v50, v42
	s_nop 0
	v_fma_f32 v34, -v42, v50, 1.0
	v_fmac_f32_e32 v50, v34, v50
	v_div_scale_f32 v34, vcc, 1.0, v38, 1.0
	v_mul_f32_e32 v46, v34, v50
	v_fma_f32 v51, -v42, v46, v34
	v_fmac_f32_e32 v46, v51, v50
	v_fma_f32 v34, -v42, v46, v34
	v_div_fmas_f32 v34, v34, v50, v46
	v_div_fixup_f32 v34, v34, v38, 1.0
	v_mov_b32_e32 v51, s26
	v_or_b32_e32 v50, s7, v84
	v_mul_f32_e32 v35, v35, v34
	v_lshlrev_b32_e32 v38, 16, v183
	v_lshlrev_b64 v[50:51], 11, v[50:51]
	v_mul_f32_e32 v35, v35, v38
	v_lshl_add_u64 v[50:51], v[96:97], 0, v[50:51]
	v_cvt_pk_bf16_f32 v35, v35, s0
	global_store_short v[50:51], v35, off
	v_mul_f32_e32 v35, v39, v34
	v_lshlrev_b32_e32 v38, 16, v182
	v_mul_f32_e32 v35, v35, v38
	v_cvt_pk_bf16_f32 v35, v35, s0
	global_store_short v[50:51], v35, off offset:32
	v_mul_f32_e32 v35, v43, v34
	v_lshlrev_b32_e32 v38, 16, v181
	v_mul_f32_e32 v35, v35, v38
	v_add_f32_e32 v38, v52, v56
	v_fmamk_f32 v38, v38, 0x3c000000, v252
	v_mul_f32_e32 v39, 0x4f800000, v38
	v_cmp_gt_f32_e32 vcc, s85, v38
	v_cvt_pk_bf16_f32 v35, v35, s0
	global_store_short v[50:51], v35, off offset:64
	v_cndmask_b32_e32 v38, v38, v39, vcc
	v_sqrt_f32_e32 v39, v38
	v_mul_f32_e32 v34, v47, v34
	v_lshlrev_b32_e32 v35, 16, v180
	v_mul_f32_e32 v34, v34, v35
	v_add_u32_e32 v42, -1, v39
	v_fma_f32 v43, -v42, v39, v38
	v_cmp_ge_f32_e64 s[62:63], 0, v43
	v_add_u32_e32 v43, 1, v39
	v_cvt_pk_bf16_f32 v34, v34, s0
	v_cndmask_b32_e64 v42, v39, v42, s[62:63]
	v_fma_f32 v39, -v43, v39, v38
	v_cmp_lt_f32_e64 s[62:63], 0, v39
	global_store_short v[50:51], v34, off offset:96
	s_nop 0
	v_cndmask_b32_e64 v39, v42, v43, s[62:63]
	v_mul_f32_e32 v42, 0x37800000, v39
	v_cndmask_b32_e32 v39, v39, v42, vcc
	v_cmp_class_f32_e32 vcc, v38, v220
	s_nop 1
	v_cndmask_b32_e32 v38, v39, v38, vcc
	v_div_scale_f32 v39, s[24:25], v38, v38, 1.0
	v_rcp_f32_e32 v42, v39
	s_nop 0
	v_fma_f32 v34, -v39, v42, 1.0
	v_fmac_f32_e32 v42, v34, v42
	v_div_scale_f32 v34, vcc, 1.0, v38, 1.0
	v_mul_f32_e32 v35, v34, v42
	v_fma_f32 v43, -v39, v35, v34
	v_fmac_f32_e32 v35, v43, v42
	v_fma_f32 v34, -v39, v35, v34
	v_div_fmas_f32 v34, v34, v42, v35
	v_div_fixup_f32 v38, v34, v38, 1.0
	v_mov_b32_e32 v35, s26
	v_or_b32_e32 v34, s7, v86
	v_mul_f32_e32 v36, v36, v38
	s_waitcnt vmcnt(15)
; __device__ __forceinline__ unsigned f2bf(float f) { return cvt_pk_bf16(f, 0.f) & 0xffffu; }
; __device__ __forceinline__ void hgrn_m3(Frame& F) {
;     ...
;         for (int r = 0; r < 4; ++r) {
;             const int t = 16 * wi + 4 * g + r;
;             const float tot = SS[t] + SS[64 + t];
;             const float rstd = 1.0f / sqrtf(tot * (1.0f / 128.0f) + RMS_EPS);
; #pragma unroll
;             for (int vt = 0; vt < 4; ++vt) HB[(t0 + t) * D + 128 * h + 64 * vh + 16 * vt + c16] = (unsigned short)f2bf(o[vt][r] * rstd * bf2f(gv[vt][r]));
;         }
;         __syncthreads();
	v_lshlrev_b32_e32 v39, 16, v179
	v_lshlrev_b64 v[34:35], 11, v[34:35]
	v_mul_f32_e32 v36, v36, v39
	v_lshl_add_u64 v[34:35], v[96:97], 0, v[34:35]
	v_cvt_pk_bf16_f32 v36, v36, s0
	global_store_short v[34:35], v36, off
	v_mul_f32_e32 v36, v40, v38
	s_waitcnt vmcnt(14)
	v_lshlrev_b32_e32 v39, 16, v178
	v_mul_f32_e32 v36, v36, v39
	v_cvt_pk_bf16_f32 v36, v36, s0
	global_store_short v[34:35], v36, off offset:32
	v_mul_f32_e32 v36, v44, v38
	s_waitcnt vmcnt(13)
	v_lshlrev_b32_e32 v39, 16, v177
	v_mul_f32_e32 v36, v36, v39
	v_add_f32_e32 v39, v53, v57
	v_fmamk_f32 v39, v39, 0x3c000000, v252
	v_mul_f32_e32 v40, 0x4f800000, v39
	v_cmp_gt_f32_e32 vcc, s85, v39
	v_cvt_pk_bf16_f32 v36, v36, s0
	global_store_short v[34:35], v36, off offset:64
	v_cndmask_b32_e32 v39, v39, v40, vcc
	v_sqrt_f32_e32 v40, v39
	v_mul_f32_e32 v36, v48, v38
	s_waitcnt vmcnt(11)
	v_lshlrev_b32_e32 v38, 16, v176
	v_mul_f32_e32 v36, v36, v38
	v_add_u32_e32 v42, -1, v40
	v_fma_f32 v43, -v42, v40, v39
	v_cmp_ge_f32_e64 s[62:63], 0, v43
	v_add_u32_e32 v43, 1, v40
	v_cvt_pk_bf16_f32 v36, v36, s0
	v_cndmask_b32_e64 v42, v40, v42, s[62:63]
	v_fma_f32 v40, -v43, v40, v39
	v_cmp_lt_f32_e64 s[62:63], 0, v40
	global_store_short v[34:35], v36, off offset:96
	v_lshlrev_b32_e32 v38, 16, v175
	v_cndmask_b32_e64 v40, v42, v43, s[62:63]
	v_mul_f32_e32 v42, 0x37800000, v40
	v_cndmask_b32_e32 v40, v40, v42, vcc
	v_cmp_class_f32_e32 vcc, v39, v220
	s_nop 1
	v_cndmask_b32_e32 v39, v40, v39, vcc
	v_div_scale_f32 v40, s[24:25], v39, v39, 1.0
	v_rcp_f32_e32 v42, v40
	s_nop 0
	v_fma_f32 v34, -v40, v42, 1.0
	v_fmac_f32_e32 v42, v34, v42
	v_div_scale_f32 v34, vcc, 1.0, v39, 1.0
	v_mul_f32_e32 v35, v34, v42
	v_fma_f32 v36, -v40, v35, v34
	v_fmac_f32_e32 v35, v36, v42
	v_fma_f32 v34, -v40, v35, v34
	v_div_fmas_f32 v34, v34, v42, v35
	v_div_fixup_f32 v36, v34, v39, 1.0
	v_mov_b32_e32 v35, s26
	v_or_b32_e32 v34, s7, v88
	v_mul_f32_e32 v37, v37, v36
	v_lshlrev_b64 v[34:35], 11, v[34:35]
	v_mul_f32_e32 v37, v37, v38
	v_lshl_add_u64 v[34:35], v[96:97], 0, v[34:35]
	v_cvt_pk_bf16_f32 v37, v37, s0
	global_store_short v[34:35], v37, off
	v_mul_f32_e32 v37, v41, v36
	v_lshlrev_b32_e32 v38, 16, v174
	v_mul_f32_e32 v37, v37, v38
	v_cvt_pk_bf16_f32 v37, v37, s0
	global_store_short v[34:35], v37, off offset:32
	v_mul_f32_e32 v37, v45, v36
	v_lshlrev_b32_e32 v38, 16, v93
	v_mul_f32_e32 v37, v37, v38
	v_cvt_pk_bf16_f32 v37, v37, s0
	global_store_short v[34:35], v37, off offset:64
	v_mul_f32_e32 v36, v49, v36
	v_lshlrev_b32_e32 v37, 16, v91
	v_mul_f32_e32 v36, v36, v37
	v_cvt_pk_bf16_f32 v36, v36, s0
	global_store_short v[34:35], v36, off offset:96
	s_cbranch_scc1 .LBB0_442
